# v47 + all waiters poll the TOP arrival counter directly (no TOPGEN publish hop on the release path)
# speedup vs baseline: 1.0031x; 1.0031x over previous
.LBB0_1163:
	s_or_b64 exec, exec, s[4:5]
	v_cvt_f32_u32_e32 v4, v2
	s_waitcnt vmcnt(0)
	v_readfirstlane_b32 s2, v3
	v_sub_u32_e32 v3, 0, v2
	v_rcp_iflag_f32_e32 v4, v4
	v_add_u32_e32 v5, s2, v1
	v_mul_f32_e32 v4, 0x4f7ffffe, v4
	v_cvt_u32_f32_e32 v4, v4
	v_mul_lo_u32 v1, v3, v4
	v_mul_hi_u32 v1, v4, v1
	v_add_u32_e32 v1, v4, v1
	v_mul_hi_u32 v1, v5, v1
	v_mul_lo_u32 v3, v1, v2
	v_sub_u32_e32 v3, v5, v3
	v_add_u32_e32 v4, 1, v1
	v_cmp_ge_u32_e32 vcc, v3, v2
	s_nop 1
	v_cndmask_b32_e32 v1, v1, v4, vcc
	v_sub_u32_e32 v4, v3, v2
	v_cndmask_b32_e32 v3, v3, v4, vcc
	v_add_u32_e32 v4, 1, v1
	v_cmp_ge_u32_e32 vcc, v3, v2
	v_add_u32_e32 v3, 1, v5
	s_nop 0
	v_cndmask_b32_e32 v1, v1, v4, vcc
	v_mul_lo_u32 v4, v2, v1
	v_add_u32_e32 v2, v4, v2
	v_cmp_ne_u32_e32 vcc, v3, v2
	s_and_saveexec_b64 s[4:5], vcc
	s_xor_b64 s[4:5], exec, s[4:5]
	s_cbranch_execz .LBB0_1177
	buffer_inv sc1
	v_readlane_b32 s6, v255, 17
	v_readlane_b32 s7, v255, 18
	s_waitcnt lgkmcnt(0)
	v_add_u32_e32 v1, 1, v1
	v_mul_lo_u32 v1, v1, v0
	s_nop 3
	global_load_dword v0, v173, s[6:7] sc1
	s_waitcnt vmcnt(0)
	v_cmp_lt_u32_e32 vcc, v0, v1
	s_and_saveexec_b64 s[6:7], vcc
	s_cbranch_execz .LBB0_1176
	s_mov_b32 s2, 1
	s_mov_b64 s[8:9], 0
	s_branch .LBB0_1167
